# attention epilogue store ladder widened: 16 dwordx2 per lane -> 8 dwordx4 via v_permlane32_swap pairs (asm guide 7.3), 4 sites, on top of v8
# baseline (speedup 1.0000x reference)
; __device__ __forceinline__ unsigned pk2(float lo, float hi) { f32x2 v = {lo, hi}; return __builtin_bit_cast(unsigned, __builtin_convertvector(v, bf16v2)); }
; DI void attn_block(const bf16_t* Q, const bf16_t* Kb, const bf16_t* Vt, bf16_t* AO, LAS unsigned char* lds, int bh, int qb, int tid, int wave, int lane) {
;     ...
;     const float inv = __builtin_amdgcn_rcpf(l + __shfl_xor(l, 32));
;     bf16_t* orow = AO + (size_t)(b * SEQ + qw + l31) * 1024 + h * 128 + 4 * hh;
; #pragma unroll
;     for (int d = 0; d < 4; ++d)
; #pragma unroll
;         for (int g4 = 0; g4 < 4; ++g4) { u32x2 w; w.x = pk2(o[d][4 * g4] * inv, o[d][4 * g4 + 1] * inv); w.y = pk2(o[d][4 * g4 + 2] * inv, o[d][4 * g4 + 3] * inv);
;             *(u32x2*)(orow + d * 32 + 8 * g4) = w; }
.LBB0_421:
	ds_bpermute_b32 v1, v200, v188
	v_lshlrev_b64 v[4:5], 11, v[186:187]
	v_lshl_add_u64 v[4:5], s[2:3], 0, v[4:5]
	s_lshl_b32 s4, s4, 1
	v_lshl_add_u64 v[4:5], v[4:5], 0, s[4:5]
	s_waitcnt lgkmcnt(0)
	v_add_f32_e32 v1, v188, v1
	v_rcp_f32_e32 v2, v1
	v_lshl_add_u64 v[4:5], v[174:175], 1, v[4:5]
	s_barrier
	v_mbcnt_lo_u32_b32 v236, -1, 0
	v_mbcnt_hi_u32_b32 v236, -1, v236
	v_and_b32_e32 v236, 32, v236
	v_lshrrev_b32_e32 v236, 2, v236
	v_mov_b32_e32 v237, 0
	v_lshl_add_u64 v[236:237], v[4:5], 0, v[236:237]
	v_pk_mul_f32 v[232:233], v[64:65], v[2:3] op_sel_hi:[1,0]
	v_pk_mul_f32 v[234:235], v[66:67], v[2:3] op_sel_hi:[1,0]
	v_cvt_pk_bf16_f32 v228, v232, v233
	v_cvt_pk_bf16_f32 v229, v234, v235
	v_pk_mul_f32 v[232:233], v[68:69], v[2:3] op_sel_hi:[1,0]
	v_pk_mul_f32 v[234:235], v[70:71], v[2:3] op_sel_hi:[1,0]
	v_cvt_pk_bf16_f32 v230, v232, v233
	v_cvt_pk_bf16_f32 v231, v234, v235
	s_nop 1
	v_permlane32_swap_b32_e32 v228, v230
	v_permlane32_swap_b32_e32 v229, v231
	global_store_dwordx4 v[236:237], v[228:231], off
	v_pk_mul_f32 v[232:233], v[72:73], v[2:3] op_sel_hi:[1,0]
	v_pk_mul_f32 v[234:235], v[74:75], v[2:3] op_sel_hi:[1,0]
	v_cvt_pk_bf16_f32 v228, v232, v233
	v_cvt_pk_bf16_f32 v229, v234, v235
	v_pk_mul_f32 v[232:233], v[76:77], v[2:3] op_sel_hi:[1,0]
	v_pk_mul_f32 v[234:235], v[78:79], v[2:3] op_sel_hi:[1,0]
	v_cvt_pk_bf16_f32 v230, v232, v233
	v_cvt_pk_bf16_f32 v231, v234, v235
	s_nop 1
	v_permlane32_swap_b32_e32 v228, v230
	v_permlane32_swap_b32_e32 v229, v231
	global_store_dwordx4 v[236:237], v[228:231], off offset:32
	v_pk_mul_f32 v[232:233], v[48:49], v[2:3] op_sel_hi:[1,0]
	v_pk_mul_f32 v[234:235], v[50:51], v[2:3] op_sel_hi:[1,0]
	v_cvt_pk_bf16_f32 v228, v232, v233
	v_cvt_pk_bf16_f32 v229, v234, v235
	v_pk_mul_f32 v[232:233], v[52:53], v[2:3] op_sel_hi:[1,0]
	v_pk_mul_f32 v[234:235], v[54:55], v[2:3] op_sel_hi:[1,0]
	v_cvt_pk_bf16_f32 v230, v232, v233
	v_cvt_pk_bf16_f32 v231, v234, v235
	s_nop 1
	v_permlane32_swap_b32_e32 v228, v230
	v_permlane32_swap_b32_e32 v229, v231
	global_store_dwordx4 v[236:237], v[228:231], off offset:64
	v_pk_mul_f32 v[232:233], v[56:57], v[2:3] op_sel_hi:[1,0]
	v_pk_mul_f32 v[234:235], v[58:59], v[2:3] op_sel_hi:[1,0]
	v_cvt_pk_bf16_f32 v228, v232, v233
	v_cvt_pk_bf16_f32 v229, v234, v235
	v_pk_mul_f32 v[232:233], v[60:61], v[2:3] op_sel_hi:[1,0]
	v_pk_mul_f32 v[234:235], v[62:63], v[2:3] op_sel_hi:[1,0]
	v_cvt_pk_bf16_f32 v230, v232, v233
	v_cvt_pk_bf16_f32 v231, v234, v235
	s_nop 1
	v_permlane32_swap_b32_e32 v228, v230
	v_permlane32_swap_b32_e32 v229, v231
	global_store_dwordx4 v[236:237], v[228:231], off offset:96
	v_pk_mul_f32 v[232:233], v[32:33], v[2:3] op_sel_hi:[1,0]
	v_pk_mul_f32 v[234:235], v[34:35], v[2:3] op_sel_hi:[1,0]
	v_cvt_pk_bf16_f32 v228, v232, v233
	v_cvt_pk_bf16_f32 v229, v234, v235
	v_pk_mul_f32 v[232:233], v[36:37], v[2:3] op_sel_hi:[1,0]
	v_pk_mul_f32 v[234:235], v[38:39], v[2:3] op_sel_hi:[1,0]
	v_cvt_pk_bf16_f32 v230, v232, v233
	v_cvt_pk_bf16_f32 v231, v234, v235
	s_nop 1
	v_permlane32_swap_b32_e32 v228, v230
	v_permlane32_swap_b32_e32 v229, v231
	global_store_dwordx4 v[236:237], v[228:231], off offset:128
	v_pk_mul_f32 v[232:233], v[40:41], v[2:3] op_sel_hi:[1,0]
	v_pk_mul_f32 v[234:235], v[42:43], v[2:3] op_sel_hi:[1,0]
	v_cvt_pk_bf16_f32 v228, v232, v233
	v_cvt_pk_bf16_f32 v229, v234, v235
	v_pk_mul_f32 v[232:233], v[44:45], v[2:3] op_sel_hi:[1,0]
	v_pk_mul_f32 v[234:235], v[46:47], v[2:3] op_sel_hi:[1,0]
	v_cvt_pk_bf16_f32 v230, v232, v233
	v_cvt_pk_bf16_f32 v231, v234, v235
	s_nop 1
	v_permlane32_swap_b32_e32 v228, v230
	v_permlane32_swap_b32_e32 v229, v231
	global_store_dwordx4 v[236:237], v[228:231], off offset:160
	v_pk_mul_f32 v[232:233], v[16:17], v[2:3] op_sel_hi:[1,0]
	v_pk_mul_f32 v[234:235], v[18:19], v[2:3] op_sel_hi:[1,0]
	v_cvt_pk_bf16_f32 v228, v232, v233
	v_cvt_pk_bf16_f32 v229, v234, v235
	v_pk_mul_f32 v[232:233], v[20:21], v[2:3] op_sel_hi:[1,0]
	v_pk_mul_f32 v[234:235], v[22:23], v[2:3] op_sel_hi:[1,0]
	v_cvt_pk_bf16_f32 v230, v232, v233
	v_cvt_pk_bf16_f32 v231, v234, v235
	s_nop 1
	v_permlane32_swap_b32_e32 v228, v230
	v_permlane32_swap_b32_e32 v229, v231
	global_store_dwordx4 v[236:237], v[228:231], off offset:192
	v_pk_mul_f32 v[232:233], v[24:25], v[2:3] op_sel_hi:[1,0]
	v_pk_mul_f32 v[234:235], v[26:27], v[2:3] op_sel_hi:[1,0]
	v_cvt_pk_bf16_f32 v228, v232, v233
	v_cvt_pk_bf16_f32 v229, v234, v235
	v_pk_mul_f32 v[232:233], v[28:29], v[2:3] op_sel_hi:[1,0]
	v_pk_mul_f32 v[234:235], v[30:31], v[2:3] op_sel_hi:[1,0]
	v_cvt_pk_bf16_f32 v230, v232, v233
	v_cvt_pk_bf16_f32 v231, v234, v235
	s_lshr_b32 s14, s74, 3
	s_add_i32 s25, s25, s78
	s_add_i32 s18, s18, s14
	s_cmp_gt_i32 s25, 63
	s_nop 1
	v_permlane32_swap_b32_e32 v228, v230
	v_permlane32_swap_b32_e32 v229, v231
	global_store_dwordx4 v[236:237], v[228:231], off offset:224
	s_cbranch_scc1 .LBB0_449

; __device__ __forceinline__ unsigned pk2(float lo, float hi) { f32x2 v = {lo, hi}; return __builtin_bit_cast(unsigned, __builtin_convertvector(v, bf16v2)); }
; #define ATT_GLOAD(kt) do { _Pragma("unroll") for (int i = 0; i < 3; ++i) kr[i] = *(const u32x4*)(Kbase + (size_t)(kt) * 64 * 192 + kgo + 64 * i); \
;         _Pragma("unroll") for (int i = 0; i < 2; ++i) vr[i] = *(const u32x4*)(Vbase + (size_t)(kt) * 64 * 2048 + vgo + 32 * i * 2048); } while (0)
; #define ATT_LSTORE(st) do { _Pragma("unroll") for (int i = 0; i < 3; ++i) *(LAS u32x4*)(lds + (st) * STG_B + klo + 128 * i) = kr[i]; \
;         _Pragma("unroll") for (int i = 0; i < 2; ++i) *(LAS u32x4*)(lds + (st) * STG_B + vlo + 32 * i * VROW_B) = vr[i]; } while (0)
; DI void attn_block(const bf16_t* Q, const bf16_t* Kb, const bf16_t* Vt, bf16_t* AO, LAS unsigned char* lds, int bh, int qb, int tid, int wave, int lane) {
;     const int b = bh >> 3, h = bh & 7, l31 = lane & 31, hh = lane >> 5;
;     const int q0 = qb * 256, qw = q0 + wave * 32, nkt = 4 * (qb + 1);
;     const bf16_t* Kbase = Kb + (size_t)bh * SEQ * 192; const bf16_t* Vbase = Vt + (size_t)b * SEQ * 2048 + h * 256 + 128;
;     bf16x8 qf[12];
;     { const bf16_t* qp = Q + (size_t)(b * SEQ + qw + l31) * 1536 + h * 192 + 8 * hh;
; #pragma unroll
;       for (int s = 0; s < 12; ++s) qf[s] = *(const bf16x8*)(qp + 16 * s); }
;     f32x16 o[4];
; #pragma unroll
;     for (int d = 0; d < 4; ++d)
; #pragma unroll
;         for (int i = 0; i < 16; ++i) o[d][i] = 0.f;
;     float m = -1e30f, l = 0.f;
;     const int kgo = (tid >> 3) * 192 + (tid & 7) * 8, klo = (tid >> 3) * KROW_B + (tid & 7) * 16;
;     const int vgo = (tid >> 4) * 2048 + (tid & 15) * 8, vlo = KT_B + (tid >> 4) * VROW_B + (tid & 15) * 16;
;     u32x4 kr[3], vr[2];
;     ...
;     ATT_GLOAD(0); ATT_LSTORE(0);
;     ...
;     const float inv = __builtin_amdgcn_rcpf(l + __shfl_xor(l, 32));
;     bf16_t* orow = AO + (size_t)(b * SEQ + qw + l31) * 1024 + h * 128 + 4 * hh;
; #pragma unroll
;     for (int d = 0; d < 4; ++d)
; #pragma unroll
;         for (int g4 = 0; g4 < 4; ++g4) { u32x2 w; w.x = pk2(o[d][4 * g4] * inv, o[d][4 * g4 + 1] * inv); w.y = pk2(o[d][4 * g4 + 2] * inv, o[d][4 * g4 + 3] * inv);
;             *(u32x2*)(orow + d * 32 + 8 * g4) = w; }
.LBB0_436:
	ds_bpermute_b32 v1, v200, v204
	v_lshlrev_b64 v[2:3], 11, v[190:191]
	v_lshl_add_u64 v[2:3], s[2:3], 0, v[2:3]
	s_lshl_b32 s4, s26, 8
	v_lshl_add_u64 v[2:3], v[2:3], 0, s[4:5]
	s_waitcnt lgkmcnt(0)
	v_add_f32_e32 v1, v204, v1
	v_rcp_f32_e32 v4, v1
	v_lshl_add_u64 v[2:3], v[174:175], 1, v[2:3]
	s_barrier
	v_mbcnt_lo_u32_b32 v236, -1, 0
	v_mbcnt_hi_u32_b32 v236, -1, v236
	v_and_b32_e32 v236, 32, v236
	v_lshrrev_b32_e32 v236, 2, v236
	v_mov_b32_e32 v237, 0
	v_lshl_add_u64 v[236:237], v[2:3], 0, v[236:237]
	v_pk_mul_f32 v[232:233], v[64:65], v[4:5] op_sel_hi:[1,0]
	v_pk_mul_f32 v[234:235], v[66:67], v[4:5] op_sel_hi:[1,0]
	v_cvt_pk_bf16_f32 v228, v232, v233
	v_cvt_pk_bf16_f32 v229, v234, v235
	v_pk_mul_f32 v[232:233], v[68:69], v[4:5] op_sel_hi:[1,0]
	v_pk_mul_f32 v[234:235], v[70:71], v[4:5] op_sel_hi:[1,0]
	v_cvt_pk_bf16_f32 v230, v232, v233
	v_cvt_pk_bf16_f32 v231, v234, v235
	s_nop 1
	v_permlane32_swap_b32_e32 v228, v230
	v_permlane32_swap_b32_e32 v229, v231
	global_store_dwordx4 v[236:237], v[228:231], off
	v_pk_mul_f32 v[232:233], v[72:73], v[4:5] op_sel_hi:[1,0]
	v_pk_mul_f32 v[234:235], v[74:75], v[4:5] op_sel_hi:[1,0]
	v_cvt_pk_bf16_f32 v228, v232, v233
	v_cvt_pk_bf16_f32 v229, v234, v235
	v_pk_mul_f32 v[232:233], v[76:77], v[4:5] op_sel_hi:[1,0]
	v_pk_mul_f32 v[234:235], v[78:79], v[4:5] op_sel_hi:[1,0]
	v_cvt_pk_bf16_f32 v230, v232, v233
	v_cvt_pk_bf16_f32 v231, v234, v235
	s_nop 1
	v_permlane32_swap_b32_e32 v228, v230
	v_permlane32_swap_b32_e32 v229, v231
	global_store_dwordx4 v[236:237], v[228:231], off offset:32
	v_pk_mul_f32 v[232:233], v[48:49], v[4:5] op_sel_hi:[1,0]
	v_pk_mul_f32 v[234:235], v[50:51], v[4:5] op_sel_hi:[1,0]
	v_cvt_pk_bf16_f32 v228, v232, v233
	v_cvt_pk_bf16_f32 v229, v234, v235
	v_pk_mul_f32 v[232:233], v[52:53], v[4:5] op_sel_hi:[1,0]
	v_pk_mul_f32 v[234:235], v[54:55], v[4:5] op_sel_hi:[1,0]
	v_cvt_pk_bf16_f32 v230, v232, v233
	v_cvt_pk_bf16_f32 v231, v234, v235
	s_nop 1
	v_permlane32_swap_b32_e32 v228, v230
	v_permlane32_swap_b32_e32 v229, v231
	global_store_dwordx4 v[236:237], v[228:231], off offset:64
	v_pk_mul_f32 v[232:233], v[56:57], v[4:5] op_sel_hi:[1,0]
	v_pk_mul_f32 v[234:235], v[58:59], v[4:5] op_sel_hi:[1,0]
	v_cvt_pk_bf16_f32 v228, v232, v233
	v_cvt_pk_bf16_f32 v229, v234, v235
	v_pk_mul_f32 v[232:233], v[60:61], v[4:5] op_sel_hi:[1,0]
	v_pk_mul_f32 v[234:235], v[62:63], v[4:5] op_sel_hi:[1,0]
	v_cvt_pk_bf16_f32 v230, v232, v233
	v_cvt_pk_bf16_f32 v231, v234, v235
	s_nop 1
	v_permlane32_swap_b32_e32 v228, v230
	v_permlane32_swap_b32_e32 v229, v231
	global_store_dwordx4 v[236:237], v[228:231], off offset:96
	v_pk_mul_f32 v[232:233], v[32:33], v[4:5] op_sel_hi:[1,0]
	v_pk_mul_f32 v[234:235], v[34:35], v[4:5] op_sel_hi:[1,0]
	v_cvt_pk_bf16_f32 v228, v232, v233
	v_cvt_pk_bf16_f32 v229, v234, v235
	v_pk_mul_f32 v[232:233], v[36:37], v[4:5] op_sel_hi:[1,0]
	v_pk_mul_f32 v[234:235], v[38:39], v[4:5] op_sel_hi:[1,0]
	v_cvt_pk_bf16_f32 v230, v232, v233
	v_cvt_pk_bf16_f32 v231, v234, v235
	s_nop 1
	v_permlane32_swap_b32_e32 v228, v230
	v_permlane32_swap_b32_e32 v229, v231
	global_store_dwordx4 v[236:237], v[228:231], off offset:128
	v_pk_mul_f32 v[232:233], v[40:41], v[4:5] op_sel_hi:[1,0]
	v_pk_mul_f32 v[234:235], v[42:43], v[4:5] op_sel_hi:[1,0]
	v_cvt_pk_bf16_f32 v228, v232, v233
	v_cvt_pk_bf16_f32 v229, v234, v235
	v_pk_mul_f32 v[232:233], v[44:45], v[4:5] op_sel_hi:[1,0]
	v_pk_mul_f32 v[234:235], v[46:47], v[4:5] op_sel_hi:[1,0]
	v_cvt_pk_bf16_f32 v230, v232, v233
	v_cvt_pk_bf16_f32 v231, v234, v235
	s_nop 1
	v_permlane32_swap_b32_e32 v228, v230
	v_permlane32_swap_b32_e32 v229, v231
	global_store_dwordx4 v[236:237], v[228:231], off offset:160
	v_pk_mul_f32 v[232:233], v[16:17], v[4:5] op_sel_hi:[1,0]
	v_pk_mul_f32 v[234:235], v[18:19], v[4:5] op_sel_hi:[1,0]
	v_cvt_pk_bf16_f32 v228, v232, v233
	v_cvt_pk_bf16_f32 v229, v234, v235
	v_pk_mul_f32 v[232:233], v[20:21], v[4:5] op_sel_hi:[1,0]
	v_pk_mul_f32 v[234:235], v[22:23], v[4:5] op_sel_hi:[1,0]
	v_cvt_pk_bf16_f32 v230, v232, v233
	v_cvt_pk_bf16_f32 v231, v234, v235
	s_nop 1
	v_permlane32_swap_b32_e32 v228, v230
	v_permlane32_swap_b32_e32 v229, v231
	global_store_dwordx4 v[236:237], v[228:231], off offset:192
	v_pk_mul_f32 v[232:233], v[24:25], v[4:5] op_sel_hi:[1,0]
	v_pk_mul_f32 v[234:235], v[26:27], v[4:5] op_sel_hi:[1,0]
	v_cvt_pk_bf16_f32 v228, v232, v233
	v_cvt_pk_bf16_f32 v229, v234, v235
	v_pk_mul_f32 v[232:233], v[28:29], v[4:5] op_sel_hi:[1,0]
	v_pk_mul_f32 v[234:235], v[30:31], v[4:5] op_sel_hi:[1,0]
	v_cvt_pk_bf16_f32 v230, v232, v233
	v_cvt_pk_bf16_f32 v231, v234, v235
	s_lshl_b32 s14, s27, 8
	s_add_i32 s14, s14, s19
	s_nop 1
	v_permlane32_swap_b32_e32 v228, v230
	v_permlane32_swap_b32_e32 v229, v231
	global_store_dwordx4 v[236:237], v[228:231], off offset:224
	s_add_i32 s4, s14, s28
	global_load_dwordx4 v[2:5], v[186:187], off
	global_load_dwordx4 v[6:9], v[186:187], off offset:128
	global_load_dwordx4 v[10:13], v[186:187], off offset:256
	s_nop 0
	global_load_dwordx4 v[14:17], v[14:15], off
	s_nop 0
	global_load_dwordx4 v[18:21], v[188:189], off
	v_or_b32_e32 v186, s4, v196
	v_mov_b64_e32 v[22:23], s[0:1]
	v_mad_i64_i32 v[22:23], s[30:31], v186, s20, v[22:23]
	s_lshl_b32 s4, s29, 1
	v_lshl_add_u64 v[22:23], v[22:23], 0, s[4:5]
	v_lshl_add_u64 v[22:23], v[168:169], 1, v[22:23]
	global_load_dwordx4 v[156:159], v[22:23], off
	global_load_dwordx4 v[152:155], v[22:23], off offset:32
	global_load_dwordx4 v[148:151], v[22:23], off offset:64
	global_load_dwordx4 v[144:147], v[22:23], off offset:96
	global_load_dwordx4 v[140:143], v[22:23], off offset:128
	global_load_dwordx4 v[136:139], v[22:23], off offset:160
	global_load_dwordx4 v[132:135], v[22:23], off offset:192
	global_load_dwordx4 v[128:131], v[22:23], off offset:224
	global_load_dwordx4 v[124:127], v[22:23], off offset:256
	global_load_dwordx4 v[120:123], v[22:23], off offset:288
	global_load_dwordx4 v[116:119], v[22:23], off offset:320
	global_load_dwordx4 v[112:115], v[22:23], off offset:352
	s_and_b32 s4, s18, 7
	s_lshl_b32 s4, s4, 8
	v_mov_b32_e32 v1, v0
	s_or_b32 s15, s4, 0xc0
	s_lshl_b32 s4, s26, 7
	v_ashrrev_i32_e32 v187, 31, v186
	s_or_b32 s26, s14, 31
	v_or_b32_e32 v190, s14, v196
	s_mov_b32 s27, 0
	v_mov_b32_e32 v189, 0xf149f2ca
	v_mov_b32_e32 v188, 0
	s_mov_b32 s28, 0
	s_waitcnt vmcnt(16)
; #define ATT_GLOAD(kt) do { _Pragma("unroll") for (int i = 0; i < 3; ++i) kr[i] = *(const u32x4*)(Kbase + (size_t)(kt) * 64 * 192 + kgo + 64 * i); \
;         _Pragma("unroll") for (int i = 0; i < 2; ++i) vr[i] = *(const u32x4*)(Vbase + (size_t)(kt) * 64 * 2048 + vgo + 32 * i * 2048); } while (0)
; #define ATT_LSTORE(st) do { _Pragma("unroll") for (int i = 0; i < 3; ++i) *(LAS u32x4*)(lds + (st) * STG_B + klo + 128 * i) = kr[i]; \
;         _Pragma("unroll") for (int i = 0; i < 2; ++i) *(LAS u32x4*)(lds + (st) * STG_B + vlo + 32 * i * VROW_B) = vr[i]; } while (0)
; DI void attn_block(const bf16_t* Q, const bf16_t* Kb, const bf16_t* Vt, bf16_t* AO, LAS unsigned char* lds, int bh, int qb, int tid, int wave, int lane) {
;     ...
;     f32x16 o[4];
; #pragma unroll
;     for (int d = 0; d < 4; ++d)
; #pragma unroll
;         for (int i = 0; i < 16; ++i) o[d][i] = 0.f;
;     float m = -1e30f, l = 0.f;
;     const int kgo = (tid >> 3) * 192 + (tid & 7) * 8, klo = (tid >> 3) * KROW_B + (tid & 7) * 16;
;     const int vgo = (tid >> 4) * 2048 + (tid & 15) * 8, vlo = KT_B + (tid >> 4) * VROW_B + (tid & 15) * 16;
;     u32x4 kr[3], vr[2];
;     ...
;     ATT_GLOAD(0); ATT_LSTORE(0);
;     __syncthreads();
	ds_write_b128 v197, v[2:5]
	s_waitcnt vmcnt(15)
	ds_write_b128 v197, v[6:9] offset:128
	s_waitcnt vmcnt(14)
	ds_write_b128 v197, v[10:13] offset:256
	s_waitcnt vmcnt(13)
	ds_write_b128 v198, v[14:17] offset:25600
	s_waitcnt vmcnt(12)
	ds_write_b128 v198, v[18:21] offset:35840
	v_mov_b32_e32 v14, v0
	v_mov_b32_e32 v15, v0
	v_mov_b32_e32 v2, v0
	v_mov_b32_e32 v3, v0
	v_mov_b32_e32 v4, v0
	v_mov_b32_e32 v5, v0
	v_mov_b32_e32 v6, v0
	v_mov_b32_e32 v7, v0
	v_mov_b32_e32 v8, v0
	v_mov_b32_e32 v9, v0
	v_mov_b32_e32 v10, v0
	v_mov_b32_e32 v11, v0
	v_mov_b32_e32 v12, v0
	v_mov_b32_e32 v13, v0
	v_mov_b64_e32 v[30:31], v[14:15]
	v_mov_b64_e32 v[46:47], v[14:15]
	v_mov_b64_e32 v[62:63], v[14:15]
	v_mov_b64_e32 v[78:79], v[14:15]
	v_mov_b64_e32 v[28:29], v[12:13]
	v_mov_b64_e32 v[26:27], v[10:11]
	v_mov_b64_e32 v[24:25], v[8:9]
	v_mov_b64_e32 v[22:23], v[6:7]
	v_mov_b64_e32 v[20:21], v[4:5]
	v_mov_b64_e32 v[18:19], v[2:3]
	v_mov_b64_e32 v[16:17], v[0:1]
	v_mov_b64_e32 v[44:45], v[12:13]
	v_mov_b64_e32 v[42:43], v[10:11]
	v_mov_b64_e32 v[40:41], v[8:9]
	v_mov_b64_e32 v[38:39], v[6:7]
	v_mov_b64_e32 v[36:37], v[4:5]
	v_mov_b64_e32 v[34:35], v[2:3]
	v_mov_b64_e32 v[32:33], v[0:1]
	v_mov_b64_e32 v[60:61], v[12:13]
	v_mov_b64_e32 v[58:59], v[10:11]
	v_mov_b64_e32 v[56:57], v[8:9]
	v_mov_b64_e32 v[54:55], v[6:7]
	v_mov_b64_e32 v[52:53], v[4:5]
	v_mov_b64_e32 v[50:51], v[2:3]
	v_mov_b64_e32 v[48:49], v[0:1]
	v_mov_b64_e32 v[76:77], v[12:13]
	v_mov_b64_e32 v[74:75], v[10:11]
	v_mov_b64_e32 v[72:73], v[8:9]
	v_mov_b64_e32 v[70:71], v[6:7]
	v_mov_b64_e32 v[68:69], v[4:5]
	v_mov_b64_e32 v[66:67], v[2:3]
	v_mov_b64_e32 v[64:65], v[0:1]
	s_waitcnt lgkmcnt(0)
	s_barrier
	s_branch .LBB0_439
